# c5 + static s_setprio 1 for waves 0-3 around GEMM main loops
# baseline (speedup 1.0000x reference)
; template <class Epi, class Sched>
; __device__ __forceinline__ void gemm_phase(LAS unsigned char* lds, const Gemm g, const Sched& S, const Epi& E, const int tid) {
;     ...
;     for (;;) {
;         const bool has_next = S.next(ui + 1, nxt);
;         const char* nA = has_next ? (const char*)g.A + (size_t)nxt.pm * tstepA : cA; const char* nB = has_next ? (const char*)g.Bt + (size_t)nxt.pn * tstepB : cB;
;         for (int t = 0; t < nt; t += 2) {
;     ...
; #pragma unroll
;         for (int a = 0; a < 2; ++a)
; #pragma unroll
;             for (int b = 0; b < 2; ++b)
; #pragma unroll
;                 for (int m = 0; m < 4; ++m)
; #pragma unroll
;                     for (int n = 0; n < 2; ++n) acc[a][b][m][n] = (f32x4){0.f, 0.f, 0.f, 0.f};
.LBB0_181:
	s_add_u32 s16, s86, 0x100
	v_mov_b32_e32 v4, 0
	s_addc_u32 s17, s87, 0
	s_mov_b32 s12, -2
	v_mov_b32_e32 v5, v4
	v_mov_b32_e32 v6, v4
	v_mov_b32_e32 v7, v4
	v_mov_b32_e32 v36, v4
	v_mov_b32_e32 v37, v4
	v_mov_b32_e32 v38, v4
	v_mov_b32_e32 v39, v4
	v_mov_b32_e32 v8, v4
	v_mov_b32_e32 v9, v4
	v_mov_b32_e32 v10, v4
	v_mov_b32_e32 v11, v4
	v_mov_b32_e32 v40, v4
	v_mov_b32_e32 v41, v4
	v_mov_b32_e32 v42, v4
	v_mov_b32_e32 v43, v4
	v_mov_b32_e32 v12, v4
	v_mov_b32_e32 v13, v4
	v_mov_b32_e32 v14, v4
	v_mov_b32_e32 v15, v4
	v_mov_b32_e32 v44, v4
	v_mov_b32_e32 v45, v4
	v_mov_b32_e32 v46, v4
	v_mov_b32_e32 v47, v4
	v_mov_b32_e32 v16, v4
	v_mov_b32_e32 v17, v4
	v_mov_b32_e32 v18, v4
	v_mov_b32_e32 v19, v4
	v_mov_b32_e32 v48, v4
	v_mov_b32_e32 v49, v4
	v_mov_b32_e32 v50, v4
	v_mov_b32_e32 v51, v4
	v_mov_b32_e32 v68, v4
	v_mov_b32_e32 v69, v4
	v_mov_b32_e32 v70, v4
	v_mov_b32_e32 v71, v4
	v_mov_b32_e32 v100, v4
	v_mov_b32_e32 v101, v4
	v_mov_b32_e32 v102, v4
	v_mov_b32_e32 v103, v4
	v_mov_b32_e32 v72, v4
	v_mov_b32_e32 v73, v4
	v_mov_b32_e32 v74, v4
	v_mov_b32_e32 v75, v4
	v_mov_b32_e32 v104, v4
	v_mov_b32_e32 v105, v4
	v_mov_b32_e32 v106, v4
	v_mov_b32_e32 v107, v4
	v_mov_b32_e32 v76, v4
	v_mov_b32_e32 v77, v4
	v_mov_b32_e32 v78, v4
	v_mov_b32_e32 v79, v4
	v_mov_b32_e32 v108, v4
	v_mov_b32_e32 v109, v4
	v_mov_b32_e32 v110, v4
	v_mov_b32_e32 v111, v4
	v_mov_b32_e32 v80, v4
	v_mov_b32_e32 v81, v4
	v_mov_b32_e32 v82, v4
	v_mov_b32_e32 v83, v4
	v_mov_b32_e32 v112, v4
	v_mov_b32_e32 v113, v4
	v_mov_b32_e32 v114, v4
	v_mov_b32_e32 v115, v4
	v_mov_b32_e32 v20, v4
	v_mov_b32_e32 v21, v4
	v_mov_b32_e32 v22, v4
	v_mov_b32_e32 v23, v4
	v_mov_b32_e32 v52, v4
	v_mov_b32_e32 v53, v4
	v_mov_b32_e32 v54, v4
	v_mov_b32_e32 v55, v4
	v_mov_b32_e32 v24, v4
	v_mov_b32_e32 v25, v4
	v_mov_b32_e32 v26, v4
	v_mov_b32_e32 v27, v4
	v_mov_b32_e32 v56, v4
	v_mov_b32_e32 v57, v4
	v_mov_b32_e32 v58, v4
	v_mov_b32_e32 v59, v4
	v_mov_b32_e32 v28, v4
	v_mov_b32_e32 v29, v4
	v_mov_b32_e32 v30, v4
	v_mov_b32_e32 v31, v4
	v_mov_b32_e32 v60, v4
	v_mov_b32_e32 v61, v4
	v_mov_b32_e32 v62, v4
	v_mov_b32_e32 v63, v4
	v_mov_b32_e32 v32, v4
	v_mov_b32_e32 v33, v4
	v_mov_b32_e32 v34, v4
	v_mov_b32_e32 v35, v4
	v_mov_b32_e32 v64, v4
	v_mov_b32_e32 v65, v4
	v_mov_b32_e32 v66, v4
	v_mov_b32_e32 v67, v4
	v_mov_b32_e32 v84, v4
	v_mov_b32_e32 v85, v4
	v_mov_b32_e32 v86, v4
	v_mov_b32_e32 v87, v4
	v_mov_b32_e32 v116, v4
	v_mov_b32_e32 v117, v4
	v_mov_b32_e32 v118, v4
	v_mov_b32_e32 v119, v4
	v_mov_b32_e32 v88, v4
	v_mov_b32_e32 v89, v4
	v_mov_b32_e32 v90, v4
	v_mov_b32_e32 v91, v4
	v_mov_b32_e32 v120, v4
	v_mov_b32_e32 v121, v4
	v_mov_b32_e32 v122, v4
	v_mov_b32_e32 v123, v4
	v_mov_b32_e32 v92, v4
	v_mov_b32_e32 v93, v4
	v_mov_b32_e32 v94, v4
	v_mov_b32_e32 v95, v4
	v_mov_b32_e32 v124, v4
	v_mov_b32_e32 v125, v4
	v_mov_b32_e32 v126, v4
	v_mov_b32_e32 v127, v4
	v_mov_b32_e32 v96, v4
	v_mov_b32_e32 v97, v4
	v_mov_b32_e32 v98, v4
	v_mov_b32_e32 v99, v4
	v_mov_b32_e32 v128, v4
	v_mov_b32_e32 v129, v4
	v_mov_b32_e32 v130, v4
	v_mov_b32_e32 v131, v4
	s_cselect_b32 s99, 1, 0
	v_readfirstlane_b32 s98, v173
	s_nop 0
	s_cmpk_gt_u32 s98, 0xff
	s_cbranch_scc1 .Lprio_skip_LBB0182
	s_setprio 1

; template <class Epi, class Sched>
; __device__ __forceinline__ void gemm_phase(LAS unsigned char* lds, const Gemm g, const Sched& S, const Epi& E, const int tid) {
;     ...
;     for (;;) {
;         const bool has_next = S.next(ui + 1, nxt);
;         const char* nA = has_next ? (const char*)g.A + (size_t)nxt.pm * tstepA : cA; const char* nB = has_next ? (const char*)g.Bt + (size_t)nxt.pn * tstepB : cB;
;         for (int t = 0; t < nt; t += 2) {
;     ...
; #pragma unroll
;         for (int a = 0; a < 2; ++a)
; #pragma unroll
;             for (int b = 0; b < 2; ++b)
; #pragma unroll
;                 for (int m = 0; m < 4; ++m)
; #pragma unroll
;                     for (int n = 0; n < 2; ++n) acc[a][b][m][n] = (f32x4){0.f, 0.f, 0.f, 0.f};
.LBB0_207:
	s_ashr_i32 s43, s42, 31
	s_lshl_b64 s[12:13], s[42:43], 20
	v_readlane_b32 s16, v255, 26
	s_add_u32 s44, s16, s12
	s_addc_u32 s45, s75, s13
	s_and_b64 s[12:13], s[6:7], exec
	s_cselect_b32 s16, s45, s55
	s_cselect_b32 s17, s44, s54
	s_ashr_i32 s39, s38, 31
	s_lshl_b64 s[12:13], s[38:39], 20
	s_add_u32 s46, s1, s12
	s_addc_u32 s47, s56, s13
	s_and_b64 s[12:13], s[6:7], exec
	s_cselect_b32 s39, s47, s87
	s_cselect_b32 s43, s46, s86
	s_add_u32 s54, s54, 0x80080
	s_addc_u32 s55, s55, 0
	s_add_u32 s93, s86, 0x100
	v_mov_b32_e32 v4, 0
	s_addc_u32 s94, s87, 0
	s_mov_b32 s95, -2
	v_mov_b32_e32 v5, v4
	v_mov_b32_e32 v6, v4
	v_mov_b32_e32 v7, v4
	v_mov_b32_e32 v8, v4
	v_mov_b32_e32 v9, v4
	v_mov_b32_e32 v10, v4
	v_mov_b32_e32 v11, v4
	v_mov_b32_e32 v12, v4
	v_mov_b32_e32 v13, v4
	v_mov_b32_e32 v14, v4
	v_mov_b32_e32 v15, v4
	v_mov_b32_e32 v16, v4
	v_mov_b32_e32 v17, v4
	v_mov_b32_e32 v18, v4
	v_mov_b32_e32 v19, v4
	v_mov_b32_e32 v28, v4
	v_mov_b32_e32 v29, v4
	v_mov_b32_e32 v30, v4
	v_mov_b32_e32 v31, v4
	v_mov_b32_e32 v32, v4
	v_mov_b32_e32 v33, v4
	v_mov_b32_e32 v34, v4
	v_mov_b32_e32 v35, v4
	v_mov_b32_e32 v44, v4
	v_mov_b32_e32 v45, v4
	v_mov_b32_e32 v46, v4
	v_mov_b32_e32 v47, v4
	v_mov_b32_e32 v48, v4
	v_mov_b32_e32 v49, v4
	v_mov_b32_e32 v50, v4
	v_mov_b32_e32 v51, v4
	v_mov_b32_e32 v20, v4
	v_mov_b32_e32 v21, v4
	v_mov_b32_e32 v22, v4
	v_mov_b32_e32 v23, v4
	v_mov_b32_e32 v24, v4
	v_mov_b32_e32 v25, v4
	v_mov_b32_e32 v26, v4
	v_mov_b32_e32 v27, v4
	v_mov_b32_e32 v36, v4
	v_mov_b32_e32 v37, v4
	v_mov_b32_e32 v38, v4
	v_mov_b32_e32 v39, v4
	v_mov_b32_e32 v40, v4
	v_mov_b32_e32 v41, v4
	v_mov_b32_e32 v42, v4
	v_mov_b32_e32 v43, v4
	v_mov_b32_e32 v52, v4
	v_mov_b32_e32 v53, v4
	v_mov_b32_e32 v54, v4
	v_mov_b32_e32 v55, v4
	v_mov_b32_e32 v56, v4
	v_mov_b32_e32 v57, v4
	v_mov_b32_e32 v58, v4
	v_mov_b32_e32 v59, v4
	v_mov_b32_e32 v60, v4
	v_mov_b32_e32 v61, v4
	v_mov_b32_e32 v62, v4
	v_mov_b32_e32 v63, v4
	v_mov_b32_e32 v64, v4
	v_mov_b32_e32 v65, v4
	v_mov_b32_e32 v66, v4
	v_mov_b32_e32 v67, v4
	v_mov_b32_e32 v68, v4
	v_mov_b32_e32 v69, v4
	v_mov_b32_e32 v70, v4
	v_mov_b32_e32 v71, v4
	v_mov_b32_e32 v72, v4
	v_mov_b32_e32 v73, v4
	v_mov_b32_e32 v74, v4
	v_mov_b32_e32 v75, v4
	v_mov_b32_e32 v76, v4
	v_mov_b32_e32 v77, v4
	v_mov_b32_e32 v78, v4
	v_mov_b32_e32 v79, v4
	v_mov_b32_e32 v80, v4
	v_mov_b32_e32 v81, v4
	v_mov_b32_e32 v82, v4
	v_mov_b32_e32 v83, v4
	v_mov_b32_e32 v92, v4
	v_mov_b32_e32 v93, v4
	v_mov_b32_e32 v94, v4
	v_mov_b32_e32 v95, v4
	v_mov_b32_e32 v96, v4
	v_mov_b32_e32 v97, v4
	v_mov_b32_e32 v98, v4
	v_mov_b32_e32 v99, v4
	v_mov_b32_e32 v108, v4
	v_mov_b32_e32 v109, v4
	v_mov_b32_e32 v110, v4
	v_mov_b32_e32 v111, v4
	v_mov_b32_e32 v112, v4
	v_mov_b32_e32 v113, v4
	v_mov_b32_e32 v114, v4
	v_mov_b32_e32 v115, v4
	v_mov_b32_e32 v84, v4
	v_mov_b32_e32 v85, v4
	v_mov_b32_e32 v86, v4
	v_mov_b32_e32 v87, v4
	v_mov_b32_e32 v88, v4
	v_mov_b32_e32 v89, v4
	v_mov_b32_e32 v90, v4
	v_mov_b32_e32 v91, v4
	v_mov_b32_e32 v100, v4
	v_mov_b32_e32 v101, v4
	v_mov_b32_e32 v102, v4
	v_mov_b32_e32 v103, v4
	v_mov_b32_e32 v104, v4
	v_mov_b32_e32 v105, v4
	v_mov_b32_e32 v106, v4
	v_mov_b32_e32 v107, v4
	v_mov_b32_e32 v116, v4
	v_mov_b32_e32 v117, v4
	v_mov_b32_e32 v118, v4
	v_mov_b32_e32 v119, v4
	v_mov_b32_e32 v120, v4
	v_mov_b32_e32 v121, v4
	v_mov_b32_e32 v122, v4
	v_mov_b32_e32 v123, v4
	v_mov_b32_e32 v124, v4
	v_mov_b32_e32 v125, v4
	v_mov_b32_e32 v126, v4
	v_mov_b32_e32 v127, v4
	v_mov_b32_e32 v128, v4
	v_mov_b32_e32 v129, v4
	v_mov_b32_e32 v130, v4
	v_mov_b32_e32 v131, v4
	s_cselect_b32 s99, 1, 0
	v_readfirstlane_b32 s98, v173
	s_nop 0
	s_cmpk_gt_u32 s98, 0xff
	s_cbranch_scc1 .Lprio_skip_LBB0208
	s_setprio 1

; template <class Epi, class Sched>
; __device__ __forceinline__ void gemm_phase(LAS unsigned char* lds, const Gemm g, const Sched& S, const Epi& E, const int tid) {
;     ...
;     for (;;) {
;         const bool has_next = S.next(ui + 1, nxt);
;         const char* nA = has_next ? (const char*)g.A + (size_t)nxt.pm * tstepA : cA; const char* nB = has_next ? (const char*)g.Bt + (size_t)nxt.pn * tstepB : cB;
;         for (int t = 0; t < nt; t += 2) {
;     ...
; #pragma unroll
;         for (int a = 0; a < 2; ++a)
; #pragma unroll
;             for (int b = 0; b < 2; ++b)
; #pragma unroll
;                 for (int m = 0; m < 4; ++m)
; #pragma unroll
;                     for (int n = 0; n < 2; ++n) acc[a][b][m][n] = (f32x4){0.f, 0.f, 0.f, 0.f};
.LBB0_250:
	s_ashr_i32 s45, s44, 31
	s_lshl_b64 s[12:13], s[44:45], 20
	s_add_u32 s54, s56, s12
	s_addc_u32 s55, s57, s13
	s_and_b64 s[8:9], s[8:9], exec
	s_cselect_b32 s17, s55, s89
	s_cselect_b32 s45, s54, s88
	s_add_u32 vcc_lo, s88, 0x100
	v_mov_b32_e32 v4, 0
	s_addc_u32 vcc_hi, s89, 0
	s_mov_b32 s12, -2
	v_mov_b32_e32 v5, v4
	v_mov_b32_e32 v6, v4
	v_mov_b32_e32 v7, v4
	v_mov_b32_e32 v36, v4
	v_mov_b32_e32 v37, v4
	v_mov_b32_e32 v38, v4
	v_mov_b32_e32 v39, v4
	v_mov_b32_e32 v8, v4
	v_mov_b32_e32 v9, v4
	v_mov_b32_e32 v10, v4
	v_mov_b32_e32 v11, v4
	v_mov_b32_e32 v40, v4
	v_mov_b32_e32 v41, v4
	v_mov_b32_e32 v42, v4
	v_mov_b32_e32 v43, v4
	v_mov_b32_e32 v12, v4
	v_mov_b32_e32 v13, v4
	v_mov_b32_e32 v14, v4
	v_mov_b32_e32 v15, v4
	v_mov_b32_e32 v44, v4
	v_mov_b32_e32 v45, v4
	v_mov_b32_e32 v46, v4
	v_mov_b32_e32 v47, v4
	v_mov_b32_e32 v16, v4
	v_mov_b32_e32 v17, v4
	v_mov_b32_e32 v18, v4
	v_mov_b32_e32 v19, v4
	v_mov_b32_e32 v48, v4
	v_mov_b32_e32 v49, v4
	v_mov_b32_e32 v50, v4
	v_mov_b32_e32 v51, v4
	v_mov_b32_e32 v68, v4
	v_mov_b32_e32 v69, v4
	v_mov_b32_e32 v70, v4
	v_mov_b32_e32 v71, v4
	v_mov_b32_e32 v100, v4
	v_mov_b32_e32 v101, v4
	v_mov_b32_e32 v102, v4
	v_mov_b32_e32 v103, v4
	v_mov_b32_e32 v72, v4
	v_mov_b32_e32 v73, v4
	v_mov_b32_e32 v74, v4
	v_mov_b32_e32 v75, v4
	v_mov_b32_e32 v104, v4
	v_mov_b32_e32 v105, v4
	v_mov_b32_e32 v106, v4
	v_mov_b32_e32 v107, v4
	v_mov_b32_e32 v76, v4
	v_mov_b32_e32 v77, v4
	v_mov_b32_e32 v78, v4
	v_mov_b32_e32 v79, v4
	v_mov_b32_e32 v108, v4
	v_mov_b32_e32 v109, v4
	v_mov_b32_e32 v110, v4
	v_mov_b32_e32 v111, v4
	v_mov_b32_e32 v80, v4
	v_mov_b32_e32 v81, v4
	v_mov_b32_e32 v82, v4
	v_mov_b32_e32 v83, v4
	v_mov_b32_e32 v112, v4
	v_mov_b32_e32 v113, v4
	v_mov_b32_e32 v114, v4
	v_mov_b32_e32 v115, v4
	v_mov_b32_e32 v20, v4
	v_mov_b32_e32 v21, v4
	v_mov_b32_e32 v22, v4
	v_mov_b32_e32 v23, v4
	v_mov_b32_e32 v52, v4
	v_mov_b32_e32 v53, v4
	v_mov_b32_e32 v54, v4
	v_mov_b32_e32 v55, v4
	v_mov_b32_e32 v24, v4
	v_mov_b32_e32 v25, v4
	v_mov_b32_e32 v26, v4
	v_mov_b32_e32 v27, v4
	v_mov_b32_e32 v56, v4
	v_mov_b32_e32 v57, v4
	v_mov_b32_e32 v58, v4
	v_mov_b32_e32 v59, v4
	v_mov_b32_e32 v28, v4
	v_mov_b32_e32 v29, v4
	v_mov_b32_e32 v30, v4
	v_mov_b32_e32 v31, v4
	v_mov_b32_e32 v60, v4
	v_mov_b32_e32 v61, v4
	v_mov_b32_e32 v62, v4
	v_mov_b32_e32 v63, v4
	v_mov_b32_e32 v32, v4
	v_mov_b32_e32 v33, v4
	v_mov_b32_e32 v34, v4
	v_mov_b32_e32 v35, v4
	v_mov_b32_e32 v64, v4
	v_mov_b32_e32 v65, v4
	v_mov_b32_e32 v66, v4
	v_mov_b32_e32 v67, v4
	v_mov_b32_e32 v84, v4
	v_mov_b32_e32 v85, v4
	v_mov_b32_e32 v86, v4
	v_mov_b32_e32 v87, v4
	v_mov_b32_e32 v116, v4
	v_mov_b32_e32 v117, v4
	v_mov_b32_e32 v118, v4
	v_mov_b32_e32 v119, v4
	v_mov_b32_e32 v88, v4
	v_mov_b32_e32 v89, v4
	v_mov_b32_e32 v90, v4
	v_mov_b32_e32 v91, v4
	v_mov_b32_e32 v120, v4
	v_mov_b32_e32 v121, v4
	v_mov_b32_e32 v122, v4
	v_mov_b32_e32 v123, v4
	v_mov_b32_e32 v92, v4
	v_mov_b32_e32 v93, v4
	v_mov_b32_e32 v94, v4
	v_mov_b32_e32 v95, v4
	v_mov_b32_e32 v124, v4
	v_mov_b32_e32 v125, v4
	v_mov_b32_e32 v126, v4
	v_mov_b32_e32 v127, v4
	v_mov_b32_e32 v96, v4
	v_mov_b32_e32 v97, v4
	v_mov_b32_e32 v98, v4
	v_mov_b32_e32 v99, v4
	v_mov_b32_e32 v128, v4
	v_mov_b32_e32 v129, v4
	v_mov_b32_e32 v130, v4
	v_mov_b32_e32 v131, v4
	s_cselect_b32 s99, 1, 0
	v_readfirstlane_b32 s98, v173
	s_nop 0
	s_cmpk_gt_u32 s98, 0xff
	s_cbranch_scc1 .Lprio_skip_LBB0251
	s_setprio 1

; template <class Epi, class Sched>
; __device__ __forceinline__ void gemm_phase(LAS unsigned char* lds, const Gemm g, const Sched& S, const Epi& E, const int tid) {
;     ...
;     for (;;) {
;         const bool has_next = S.next(ui + 1, nxt);
;         const char* nA = has_next ? (const char*)g.A + (size_t)nxt.pm * tstepA : cA; const char* nB = has_next ? (const char*)g.Bt + (size_t)nxt.pn * tstepB : cB;
;         for (int t = 0; t < nt; t += 2) {
;     ...
; #pragma unroll
;         for (int a = 0; a < 2; ++a)
; #pragma unroll
;             for (int b = 0; b < 2; ++b)
; #pragma unroll
;                 for (int m = 0; m < 4; ++m)
; #pragma unroll
;                     for (int n = 0; n < 2; ++n) acc[a][b][m][n] = (f32x4){0.f, 0.f, 0.f, 0.f};
.LBB0_278:
	s_ashr_i32 s31, s30, 31
	s_lshl_b64 s[12:13], s[30:31], 20
	s_add_u32 s42, s56, s12
	s_addc_u32 s43, s57, s13
	s_and_b64 s[8:9], s[8:9], exec
	s_cselect_b32 s16, s43, s47
	s_cselect_b32 s17, s42, s46
	s_add_u32 s31, s46, 0x100
	v_mov_b32_e32 v4, 0
	s_addc_u32 s93, s47, 0
	s_mov_b32 s94, -2
	v_mov_b32_e32 v5, v4
	v_mov_b32_e32 v6, v4
	v_mov_b32_e32 v7, v4
	v_mov_b32_e32 v36, v4
	v_mov_b32_e32 v37, v4
	v_mov_b32_e32 v38, v4
	v_mov_b32_e32 v39, v4
	v_mov_b32_e32 v8, v4
	v_mov_b32_e32 v9, v4
	v_mov_b32_e32 v10, v4
	v_mov_b32_e32 v11, v4
	v_mov_b32_e32 v40, v4
	v_mov_b32_e32 v41, v4
	v_mov_b32_e32 v42, v4
	v_mov_b32_e32 v43, v4
	v_mov_b32_e32 v12, v4
	v_mov_b32_e32 v13, v4
	v_mov_b32_e32 v14, v4
	v_mov_b32_e32 v15, v4
	v_mov_b32_e32 v44, v4
	v_mov_b32_e32 v45, v4
	v_mov_b32_e32 v46, v4
	v_mov_b32_e32 v47, v4
	v_mov_b32_e32 v16, v4
	v_mov_b32_e32 v17, v4
	v_mov_b32_e32 v18, v4
	v_mov_b32_e32 v19, v4
	v_mov_b32_e32 v48, v4
	v_mov_b32_e32 v49, v4
	v_mov_b32_e32 v50, v4
	v_mov_b32_e32 v51, v4
	v_mov_b32_e32 v68, v4
	v_mov_b32_e32 v69, v4
	v_mov_b32_e32 v70, v4
	v_mov_b32_e32 v71, v4
	v_mov_b32_e32 v100, v4
	v_mov_b32_e32 v101, v4
	v_mov_b32_e32 v102, v4
	v_mov_b32_e32 v103, v4
	v_mov_b32_e32 v72, v4
	v_mov_b32_e32 v73, v4
	v_mov_b32_e32 v74, v4
	v_mov_b32_e32 v75, v4
	v_mov_b32_e32 v104, v4
	v_mov_b32_e32 v105, v4
	v_mov_b32_e32 v106, v4
	v_mov_b32_e32 v107, v4
	v_mov_b32_e32 v76, v4
	v_mov_b32_e32 v77, v4
	v_mov_b32_e32 v78, v4
	v_mov_b32_e32 v79, v4
	v_mov_b32_e32 v108, v4
	v_mov_b32_e32 v109, v4
	v_mov_b32_e32 v110, v4
	v_mov_b32_e32 v111, v4
	v_mov_b32_e32 v80, v4
	v_mov_b32_e32 v81, v4
	v_mov_b32_e32 v82, v4
	v_mov_b32_e32 v83, v4
	v_mov_b32_e32 v112, v4
	v_mov_b32_e32 v113, v4
	v_mov_b32_e32 v114, v4
	v_mov_b32_e32 v115, v4
	v_mov_b32_e32 v20, v4
	v_mov_b32_e32 v21, v4
	v_mov_b32_e32 v22, v4
	v_mov_b32_e32 v23, v4
	v_mov_b32_e32 v52, v4
	v_mov_b32_e32 v53, v4
	v_mov_b32_e32 v54, v4
	v_mov_b32_e32 v55, v4
	v_mov_b32_e32 v24, v4
	v_mov_b32_e32 v25, v4
	v_mov_b32_e32 v26, v4
	v_mov_b32_e32 v27, v4
	v_mov_b32_e32 v56, v4
	v_mov_b32_e32 v57, v4
	v_mov_b32_e32 v58, v4
	v_mov_b32_e32 v59, v4
	v_mov_b32_e32 v28, v4
	v_mov_b32_e32 v29, v4
	v_mov_b32_e32 v30, v4
	v_mov_b32_e32 v31, v4
	v_mov_b32_e32 v60, v4
	v_mov_b32_e32 v61, v4
	v_mov_b32_e32 v62, v4
	v_mov_b32_e32 v63, v4
	v_mov_b32_e32 v32, v4
	v_mov_b32_e32 v33, v4
	v_mov_b32_e32 v34, v4
	v_mov_b32_e32 v35, v4
	v_mov_b32_e32 v64, v4
	v_mov_b32_e32 v65, v4
	v_mov_b32_e32 v66, v4
	v_mov_b32_e32 v67, v4
	v_mov_b32_e32 v84, v4
	v_mov_b32_e32 v85, v4
	v_mov_b32_e32 v86, v4
	v_mov_b32_e32 v87, v4
	v_mov_b32_e32 v116, v4
	v_mov_b32_e32 v117, v4
	v_mov_b32_e32 v118, v4
	v_mov_b32_e32 v119, v4
	v_mov_b32_e32 v88, v4
	v_mov_b32_e32 v89, v4
	v_mov_b32_e32 v90, v4
	v_mov_b32_e32 v91, v4
	v_mov_b32_e32 v120, v4
	v_mov_b32_e32 v121, v4
	v_mov_b32_e32 v122, v4
	v_mov_b32_e32 v123, v4
	v_mov_b32_e32 v92, v4
	v_mov_b32_e32 v93, v4
	v_mov_b32_e32 v94, v4
	v_mov_b32_e32 v95, v4
	v_mov_b32_e32 v124, v4
	v_mov_b32_e32 v125, v4
	v_mov_b32_e32 v126, v4
	v_mov_b32_e32 v127, v4
	v_mov_b32_e32 v96, v4
	v_mov_b32_e32 v97, v4
	v_mov_b32_e32 v98, v4
	v_mov_b32_e32 v99, v4
	v_mov_b32_e32 v128, v4
	v_mov_b32_e32 v129, v4
	v_mov_b32_e32 v130, v4
	v_mov_b32_e32 v131, v4
	s_cselect_b32 s99, 1, 0
	v_readfirstlane_b32 s98, v173
	s_nop 0
	s_cmpk_gt_u32 s98, 0xff
	s_cbranch_scc1 .Lprio_skip_LBB0279
	s_setprio 1

; template <class Epi, class Sched>
; __device__ __forceinline__ void gemm_phase(LAS unsigned char* lds, const Gemm g, const Sched& S, const Epi& E, const int tid) {
;     ...
;     for (;;) {
;         const bool has_next = S.next(ui + 1, nxt);
;         const char* nA = has_next ? (const char*)g.A + (size_t)nxt.pm * tstepA : cA; const char* nB = has_next ? (const char*)g.Bt + (size_t)nxt.pn * tstepB : cB;
;         for (int t = 0; t < nt; t += 2) {
;     ...
; #pragma unroll
;         for (int a = 0; a < 2; ++a)
; #pragma unroll
;             for (int b = 0; b < 2; ++b)
; #pragma unroll
;                 for (int m = 0; m < 4; ++m)
; #pragma unroll
;                     for (int n = 0; n < 2; ++n) acc[a][b][m][n] = (f32x4){0.f, 0.f, 0.f, 0.f};
.LBB0_307:
	s_ashr_i32 s39, s38, 31
	s_lshl_b64 s[12:13], s[38:39], 19
	s_add_u32 s42, s26, s12
	s_addc_u32 s43, s56, s13
	s_and_b64 s[12:13], s[6:7], exec
	s_cselect_b32 s16, s43, s55
	s_cselect_b32 s17, s42, s54
	s_ashr_i32 s31, s30, 31
	s_lshl_b64 s[12:13], s[30:31], 19
	s_add_u32 s44, s57, s12
	s_addc_u32 s45, s58, s13
	s_and_b64 s[12:13], s[6:7], exec
	s_cselect_b32 s31, s45, s91
	s_cselect_b32 s39, s44, s90
	s_add_u32 s54, s54, 0x40080
	s_addc_u32 s55, s55, 0
	s_add_u32 s47, s90, 0x100
	v_mov_b32_e32 v4, 0
	s_addc_u32 s96, s91, 0
	s_mov_b32 s97, -2
	v_mov_b32_e32 v5, v4
	v_mov_b32_e32 v6, v4
	v_mov_b32_e32 v7, v4
	v_mov_b32_e32 v8, v4
	v_mov_b32_e32 v9, v4
	v_mov_b32_e32 v10, v4
	v_mov_b32_e32 v11, v4
	v_mov_b32_e32 v16, v4
	v_mov_b32_e32 v17, v4
	v_mov_b32_e32 v18, v4
	v_mov_b32_e32 v19, v4
	v_mov_b32_e32 v24, v4
	v_mov_b32_e32 v25, v4
	v_mov_b32_e32 v26, v4
	v_mov_b32_e32 v27, v4
	v_mov_b32_e32 v36, v4
	v_mov_b32_e32 v37, v4
	v_mov_b32_e32 v38, v4
	v_mov_b32_e32 v39, v4
	v_mov_b32_e32 v40, v4
	v_mov_b32_e32 v41, v4
	v_mov_b32_e32 v42, v4
	v_mov_b32_e32 v43, v4
	v_mov_b32_e32 v44, v4
	v_mov_b32_e32 v45, v4
	v_mov_b32_e32 v46, v4
	v_mov_b32_e32 v47, v4
	v_mov_b32_e32 v52, v4
	v_mov_b32_e32 v53, v4
	v_mov_b32_e32 v54, v4
	v_mov_b32_e32 v55, v4
	v_mov_b32_e32 v12, v4
	v_mov_b32_e32 v13, v4
	v_mov_b32_e32 v14, v4
	v_mov_b32_e32 v15, v4
	v_mov_b32_e32 v20, v4
	v_mov_b32_e32 v21, v4
	v_mov_b32_e32 v22, v4
	v_mov_b32_e32 v23, v4
	v_mov_b32_e32 v28, v4
	v_mov_b32_e32 v29, v4
	v_mov_b32_e32 v30, v4
	v_mov_b32_e32 v31, v4
	v_mov_b32_e32 v32, v4
	v_mov_b32_e32 v33, v4
	v_mov_b32_e32 v34, v4
	v_mov_b32_e32 v35, v4
	v_mov_b32_e32 v48, v4
	v_mov_b32_e32 v49, v4
	v_mov_b32_e32 v50, v4
	v_mov_b32_e32 v51, v4
	v_mov_b32_e32 v56, v4
	v_mov_b32_e32 v57, v4
	v_mov_b32_e32 v58, v4
	v_mov_b32_e32 v59, v4
	v_mov_b32_e32 v60, v4
	v_mov_b32_e32 v61, v4
	v_mov_b32_e32 v62, v4
	v_mov_b32_e32 v63, v4
	v_mov_b32_e32 v64, v4
	v_mov_b32_e32 v65, v4
	v_mov_b32_e32 v66, v4
	v_mov_b32_e32 v67, v4
	v_mov_b32_e32 v68, v4
	v_mov_b32_e32 v69, v4
	v_mov_b32_e32 v70, v4
	v_mov_b32_e32 v71, v4
	v_mov_b32_e32 v72, v4
	v_mov_b32_e32 v73, v4
	v_mov_b32_e32 v74, v4
	v_mov_b32_e32 v75, v4
	v_mov_b32_e32 v76, v4
	v_mov_b32_e32 v77, v4
	v_mov_b32_e32 v78, v4
	v_mov_b32_e32 v79, v4
	v_mov_b32_e32 v84, v4
	v_mov_b32_e32 v85, v4
	v_mov_b32_e32 v86, v4
	v_mov_b32_e32 v87, v4
	v_mov_b32_e32 v100, v4
	v_mov_b32_e32 v101, v4
	v_mov_b32_e32 v102, v4
	v_mov_b32_e32 v103, v4
	v_mov_b32_e32 v104, v4
	v_mov_b32_e32 v105, v4
	v_mov_b32_e32 v106, v4
	v_mov_b32_e32 v107, v4
	v_mov_b32_e32 v108, v4
	v_mov_b32_e32 v109, v4
	v_mov_b32_e32 v110, v4
	v_mov_b32_e32 v111, v4
	v_mov_b32_e32 v116, v4
	v_mov_b32_e32 v117, v4
	v_mov_b32_e32 v118, v4
	v_mov_b32_e32 v119, v4
	v_mov_b32_e32 v80, v4
	v_mov_b32_e32 v81, v4
	v_mov_b32_e32 v82, v4
	v_mov_b32_e32 v83, v4
	v_mov_b32_e32 v88, v4
	v_mov_b32_e32 v89, v4
	v_mov_b32_e32 v90, v4
	v_mov_b32_e32 v91, v4
	v_mov_b32_e32 v92, v4
	v_mov_b32_e32 v93, v4
	v_mov_b32_e32 v94, v4
	v_mov_b32_e32 v95, v4
	v_mov_b32_e32 v96, v4
	v_mov_b32_e32 v97, v4
	v_mov_b32_e32 v98, v4
	v_mov_b32_e32 v99, v4
	v_mov_b32_e32 v112, v4
	v_mov_b32_e32 v113, v4
	v_mov_b32_e32 v114, v4
	v_mov_b32_e32 v115, v4
	v_mov_b32_e32 v120, v4
	v_mov_b32_e32 v121, v4
	v_mov_b32_e32 v122, v4
	v_mov_b32_e32 v123, v4
	v_mov_b32_e32 v124, v4
	v_mov_b32_e32 v125, v4
	v_mov_b32_e32 v126, v4
	v_mov_b32_e32 v127, v4
	v_mov_b32_e32 v128, v4
	v_mov_b32_e32 v129, v4
	v_mov_b32_e32 v130, v4
	v_mov_b32_e32 v131, v4
	s_cselect_b32 s99, 1, 0
	v_readfirstlane_b32 s98, v173
	s_nop 0
	s_cmpk_gt_u32 s98, 0xff
	s_cbranch_scc1 .Lprio_skip_LBB0308
	s_setprio 1

; template <class Epi, class Sched>
; __device__ __forceinline__ void gemm_phase(LAS unsigned char* lds, const Gemm g, const Sched& S, const Epi& E, const int tid) {
;     ...
;     for (;;) {
;         const bool has_next = S.next(ui + 1, nxt);
;         const char* nA = has_next ? (const char*)g.A + (size_t)nxt.pm * tstepA : cA; const char* nB = has_next ? (const char*)g.Bt + (size_t)nxt.pn * tstepB : cB;
;         for (int t = 0; t < nt; t += 2) {
;     ...
; #pragma unroll
;         for (int a = 0; a < 2; ++a)
; #pragma unroll
;             for (int b = 0; b < 2; ++b)
; #pragma unroll
;                 for (int m = 0; m < 4; ++m)
; #pragma unroll
;                     for (int n = 0; n < 2; ++n) acc[a][b][m][n] = (f32x4){0.f, 0.f, 0.f, 0.f};
.LBB0_331:
	s_ashr_i32 s39, s38, 31
	s_lshl_b64 s[12:13], s[38:39], 19
	s_add_u32 s42, s26, s12
	s_addc_u32 s43, s56, s13
	s_and_b64 s[12:13], s[6:7], exec
	s_cselect_b32 s16, s43, s55
	s_cselect_b32 s17, s42, s54
	s_ashr_i32 s31, s30, 31
	s_lshl_b64 s[12:13], s[30:31], 19
	s_add_u32 s44, s57, s12
	s_addc_u32 s45, s58, s13
	s_and_b64 s[12:13], s[6:7], exec
	s_cselect_b32 s31, s45, s91
	s_cselect_b32 s39, s44, s90
	s_add_u32 s54, s54, 0x40080
	s_addc_u32 s55, s55, 0
	s_add_u32 s47, s90, 0x100
	v_mov_b32_e32 v4, 0
	s_addc_u32 s96, s91, 0
	s_mov_b32 s97, -2
	v_mov_b32_e32 v5, v4
	v_mov_b32_e32 v6, v4
	v_mov_b32_e32 v7, v4
	v_mov_b32_e32 v8, v4
	v_mov_b32_e32 v9, v4
	v_mov_b32_e32 v10, v4
	v_mov_b32_e32 v11, v4
	v_mov_b32_e32 v20, v4
	v_mov_b32_e32 v21, v4
	v_mov_b32_e32 v22, v4
	v_mov_b32_e32 v23, v4
	v_mov_b32_e32 v24, v4
	v_mov_b32_e32 v25, v4
	v_mov_b32_e32 v26, v4
	v_mov_b32_e32 v27, v4
	v_mov_b32_e32 v36, v4
	v_mov_b32_e32 v37, v4
	v_mov_b32_e32 v38, v4
	v_mov_b32_e32 v39, v4
	v_mov_b32_e32 v40, v4
	v_mov_b32_e32 v41, v4
	v_mov_b32_e32 v42, v4
	v_mov_b32_e32 v43, v4
	v_mov_b32_e32 v52, v4
	v_mov_b32_e32 v53, v4
	v_mov_b32_e32 v54, v4
	v_mov_b32_e32 v55, v4
	v_mov_b32_e32 v56, v4
	v_mov_b32_e32 v57, v4
	v_mov_b32_e32 v58, v4
	v_mov_b32_e32 v59, v4
	v_mov_b32_e32 v12, v4
	v_mov_b32_e32 v13, v4
	v_mov_b32_e32 v14, v4
	v_mov_b32_e32 v15, v4
	v_mov_b32_e32 v16, v4
	v_mov_b32_e32 v17, v4
	v_mov_b32_e32 v18, v4
	v_mov_b32_e32 v19, v4
	v_mov_b32_e32 v28, v4
	v_mov_b32_e32 v29, v4
	v_mov_b32_e32 v30, v4
	v_mov_b32_e32 v31, v4
	v_mov_b32_e32 v32, v4
	v_mov_b32_e32 v33, v4
	v_mov_b32_e32 v34, v4
	v_mov_b32_e32 v35, v4
	v_mov_b32_e32 v44, v4
	v_mov_b32_e32 v45, v4
	v_mov_b32_e32 v46, v4
	v_mov_b32_e32 v47, v4
	v_mov_b32_e32 v48, v4
	v_mov_b32_e32 v49, v4
	v_mov_b32_e32 v50, v4
	v_mov_b32_e32 v51, v4
	v_mov_b32_e32 v60, v4
	v_mov_b32_e32 v61, v4
	v_mov_b32_e32 v62, v4
	v_mov_b32_e32 v63, v4
	v_mov_b32_e32 v64, v4
	v_mov_b32_e32 v65, v4
	v_mov_b32_e32 v66, v4
	v_mov_b32_e32 v67, v4
	v_mov_b32_e32 v68, v4
	v_mov_b32_e32 v69, v4
	v_mov_b32_e32 v70, v4
	v_mov_b32_e32 v71, v4
	v_mov_b32_e32 v72, v4
	v_mov_b32_e32 v73, v4
	v_mov_b32_e32 v74, v4
	v_mov_b32_e32 v75, v4
	v_mov_b32_e32 v84, v4
	v_mov_b32_e32 v85, v4
	v_mov_b32_e32 v86, v4
	v_mov_b32_e32 v87, v4
	v_mov_b32_e32 v88, v4
	v_mov_b32_e32 v89, v4
	v_mov_b32_e32 v90, v4
	v_mov_b32_e32 v91, v4
	v_mov_b32_e32 v100, v4
	v_mov_b32_e32 v101, v4
	v_mov_b32_e32 v102, v4
	v_mov_b32_e32 v103, v4
	v_mov_b32_e32 v104, v4
	v_mov_b32_e32 v105, v4
	v_mov_b32_e32 v106, v4
	v_mov_b32_e32 v107, v4
	v_mov_b32_e32 v116, v4
	v_mov_b32_e32 v117, v4
	v_mov_b32_e32 v118, v4
	v_mov_b32_e32 v119, v4
	v_mov_b32_e32 v120, v4
	v_mov_b32_e32 v121, v4
	v_mov_b32_e32 v122, v4
	v_mov_b32_e32 v123, v4
	v_mov_b32_e32 v76, v4
	v_mov_b32_e32 v77, v4
	v_mov_b32_e32 v78, v4
	v_mov_b32_e32 v79, v4
	v_mov_b32_e32 v80, v4
	v_mov_b32_e32 v81, v4
	v_mov_b32_e32 v82, v4
	v_mov_b32_e32 v83, v4
	v_mov_b32_e32 v92, v4
	v_mov_b32_e32 v93, v4
	v_mov_b32_e32 v94, v4
	v_mov_b32_e32 v95, v4
	v_mov_b32_e32 v96, v4
	v_mov_b32_e32 v97, v4
	v_mov_b32_e32 v98, v4
	v_mov_b32_e32 v99, v4
	v_mov_b32_e32 v108, v4
	v_mov_b32_e32 v109, v4
	v_mov_b32_e32 v110, v4
	v_mov_b32_e32 v111, v4
	v_mov_b32_e32 v112, v4
	v_mov_b32_e32 v113, v4
	v_mov_b32_e32 v114, v4
	v_mov_b32_e32 v115, v4
	v_mov_b32_e32 v124, v4
	v_mov_b32_e32 v125, v4
	v_mov_b32_e32 v126, v4
	v_mov_b32_e32 v127, v4
	v_mov_b32_e32 v128, v4
	v_mov_b32_e32 v129, v4
	v_mov_b32_e32 v130, v4
	v_mov_b32_e32 v131, v4
	s_cselect_b32 s99, 1, 0
	v_readfirstlane_b32 s98, v173
	s_nop 0
	s_cmpk_gt_u32 s98, 0xff
	s_cbranch_scc1 .Lprio_skip_LBB0332
	s_setprio 1

; template <class Epi, class Sched>
; __device__ __forceinline__ void gemm_phase(LAS unsigned char* lds, const Gemm g, const Sched& S, const Epi& E, const int tid) {
;     ...
;     for (;;) {
;         const bool has_next = S.next(ui + 1, nxt);
;         const char* nA = has_next ? (const char*)g.A + (size_t)nxt.pm * tstepA : cA; const char* nB = has_next ? (const char*)g.Bt + (size_t)nxt.pn * tstepB : cB;
;         for (int t = 0; t < nt; t += 2) {
;     ...
; #pragma unroll
;         for (int a = 0; a < 2; ++a)
; #pragma unroll
;             for (int b = 0; b < 2; ++b)
; #pragma unroll
;                 for (int m = 0; m < 4; ++m)
; #pragma unroll
;                     for (int n = 0; n < 2; ++n) acc[a][b][m][n] = (f32x4){0.f, 0.f, 0.f, 0.f};
.LBB0_588:
	s_ashr_i32 s39, s38, 31
	s_lshl_b64 s[42:43], s[38:39], 20
	v_readlane_b32 s0, v255, 26
	s_add_u32 s42, s0, s42
	s_addc_u32 s43, s75, s43
	s_and_b64 s[44:45], s[6:7], exec
	s_cselect_b32 s0, s43, s47
	s_cselect_b32 s9, s42, s46
	s_ashr_i32 s31, s30, 31
	s_lshl_b64 s[44:45], s[30:31], 20
	s_add_u32 s44, s80, s44
	s_addc_u32 s45, s81, s45
	s_and_b64 s[84:85], s[6:7], exec
	s_cselect_b32 s11, s45, s55
	s_cselect_b32 s31, s44, s54
	s_add_u32 s46, s46, 0x80080
	s_addc_u32 s47, s47, 0
	s_add_u32 s39, s54, 0x100
	v_mov_b32_e32 v4, 0
	s_addc_u32 s86, s55, 0
	s_mov_b32 s87, -2
	v_mov_b32_e32 v5, v4
	v_mov_b32_e32 v6, v4
	v_mov_b32_e32 v7, v4
	v_mov_b32_e32 v8, v4
	v_mov_b32_e32 v9, v4
	v_mov_b32_e32 v10, v4
	v_mov_b32_e32 v11, v4
	v_mov_b32_e32 v12, v4
	v_mov_b32_e32 v13, v4
	v_mov_b32_e32 v14, v4
	v_mov_b32_e32 v15, v4
	v_mov_b32_e32 v16, v4
	v_mov_b32_e32 v17, v4
	v_mov_b32_e32 v18, v4
	v_mov_b32_e32 v19, v4
	v_mov_b32_e32 v20, v4
	v_mov_b32_e32 v21, v4
	v_mov_b32_e32 v22, v4
	v_mov_b32_e32 v23, v4
	v_mov_b32_e32 v24, v4
	v_mov_b32_e32 v25, v4
	v_mov_b32_e32 v26, v4
	v_mov_b32_e32 v27, v4
	v_mov_b32_e32 v28, v4
	v_mov_b32_e32 v29, v4
	v_mov_b32_e32 v30, v4
	v_mov_b32_e32 v31, v4
	v_mov_b32_e32 v32, v4
	v_mov_b32_e32 v33, v4
	v_mov_b32_e32 v34, v4
	v_mov_b32_e32 v35, v4
	v_mov_b32_e32 v68, v4
	v_mov_b32_e32 v69, v4
	v_mov_b32_e32 v70, v4
	v_mov_b32_e32 v71, v4
	v_mov_b32_e32 v72, v4
	v_mov_b32_e32 v73, v4
	v_mov_b32_e32 v74, v4
	v_mov_b32_e32 v75, v4
	v_mov_b32_e32 v76, v4
	v_mov_b32_e32 v77, v4
	v_mov_b32_e32 v78, v4
	v_mov_b32_e32 v79, v4
	v_mov_b32_e32 v80, v4
	v_mov_b32_e32 v81, v4
	v_mov_b32_e32 v82, v4
	v_mov_b32_e32 v83, v4
	v_mov_b32_e32 v84, v4
	v_mov_b32_e32 v85, v4
	v_mov_b32_e32 v86, v4
	v_mov_b32_e32 v87, v4
	v_mov_b32_e32 v88, v4
	v_mov_b32_e32 v89, v4
	v_mov_b32_e32 v90, v4
	v_mov_b32_e32 v91, v4
	v_mov_b32_e32 v92, v4
	v_mov_b32_e32 v93, v4
	v_mov_b32_e32 v94, v4
	v_mov_b32_e32 v95, v4
	v_mov_b32_e32 v96, v4
	v_mov_b32_e32 v97, v4
	v_mov_b32_e32 v98, v4
	v_mov_b32_e32 v99, v4
	v_mov_b32_e32 v36, v4
	v_mov_b32_e32 v37, v4
	v_mov_b32_e32 v38, v4
	v_mov_b32_e32 v39, v4
	v_mov_b32_e32 v40, v4
	v_mov_b32_e32 v41, v4
	v_mov_b32_e32 v42, v4
	v_mov_b32_e32 v43, v4
	v_mov_b32_e32 v44, v4
	v_mov_b32_e32 v45, v4
	v_mov_b32_e32 v46, v4
	v_mov_b32_e32 v47, v4
	v_mov_b32_e32 v48, v4
	v_mov_b32_e32 v49, v4
	v_mov_b32_e32 v50, v4
	v_mov_b32_e32 v51, v4
	v_mov_b32_e32 v52, v4
	v_mov_b32_e32 v53, v4
	v_mov_b32_e32 v54, v4
	v_mov_b32_e32 v55, v4
	v_mov_b32_e32 v56, v4
	v_mov_b32_e32 v57, v4
	v_mov_b32_e32 v58, v4
	v_mov_b32_e32 v59, v4
	v_mov_b32_e32 v60, v4
	v_mov_b32_e32 v61, v4
	v_mov_b32_e32 v62, v4
	v_mov_b32_e32 v63, v4
	v_mov_b32_e32 v64, v4
	v_mov_b32_e32 v65, v4
	v_mov_b32_e32 v66, v4
	v_mov_b32_e32 v67, v4
	v_mov_b32_e32 v108, v4
	v_mov_b32_e32 v109, v4
	v_mov_b32_e32 v110, v4
	v_mov_b32_e32 v111, v4
	v_mov_b32_e32 v112, v4
	v_mov_b32_e32 v113, v4
	v_mov_b32_e32 v114, v4
	v_mov_b32_e32 v115, v4
	v_mov_b32_e32 v116, v4
	v_mov_b32_e32 v117, v4
	v_mov_b32_e32 v118, v4
	v_mov_b32_e32 v119, v4
	v_mov_b32_e32 v120, v4
	v_mov_b32_e32 v121, v4
	v_mov_b32_e32 v122, v4
	v_mov_b32_e32 v123, v4
	v_mov_b32_e32 v124, v4
	v_mov_b32_e32 v125, v4
	v_mov_b32_e32 v126, v4
	v_mov_b32_e32 v127, v4
	v_mov_b32_e32 v128, v4
	v_mov_b32_e32 v129, v4
	v_mov_b32_e32 v130, v4
	v_mov_b32_e32 v131, v4
	v_mov_b32_e32 v132, v4
	v_mov_b32_e32 v133, v4
	v_mov_b32_e32 v134, v4
	v_mov_b32_e32 v135, v4
	v_mov_b32_e32 v136, v4
	v_mov_b32_e32 v137, v4
	v_mov_b32_e32 v138, v4
	v_mov_b32_e32 v139, v4
	s_cselect_b32 s99, 1, 0
	v_readfirstlane_b32 s98, v173
	s_nop 0
	s_cmpk_gt_u32 s98, 0xff
	s_cbranch_scc1 .Lprio_skip_LBB0589
	s_setprio 1
